# nmk MFMA order + dt tasks: next item's A fragments requested before the softplus epilogue
# baseline (speedup 1.0000x reference)
; __device__ __forceinline__ void ph_dt_tasks(Frame& F, int layer) {
;     ...
;     for (int it = bid; it < M / 32; it += F.G) {
;         const int row0 = 32 * it + 16 * (wave >> 2);
;         const bf16* ap = pA2 + (size_t)(row0 + r) * D + kq * 512 + 8 * g;
;         bf16x8 av[16];
; #pragma unroll
;         for (int ks = 0; ks < 16; ++ks) av[ks] = *(const bf16x8*)(ap + 32 * ks);
;         f32x4 a0 = {0.f, 0.f, 0.f, 0.f}, a1 = a0;
; #pragma unroll
;         for (int ks = 0; ks < 16; ++ks) { a0 = __builtin_amdgcn_mfma_f32_16x16x32_bf16(av[ks], wv0[ks], a0, 0, 0, 0); a1 = __builtin_amdgcn_mfma_f32_16x16x32_bf16(av[ks], wv1[ks], a1, 0, 0, 0); }
;         red[(wave * 2 + 0) * 64 + lane] = a0; red[(wave * 2 + 1) * 64 + lane] = a1;
;         __syncthreads();
;         if (kq == 0) {
; #pragma unroll
;             for (int k = 1; k < 4; ++k) { a0 += red[((wave + k) * 2 + 0) * 64 + lane]; a1 += red[((wave + k) * 2 + 1) * 64 + lane]; }
; #pragma unroll
;             for (int q = 0; q < 4; ++q) { float* o = pDT + (size_t)(row0 + 4 * g + q) * 32 + r; const float x0 = a0[q] + b0, x1 = a1[q] + b1;
;                 o[0] = fmaxf(x0, 0.f) + log1pf(__expf(-fabsf(x0))); o[16] = fmaxf(x1, 0.f) + log1pf(__expf(-fabsf(x1))); }
;         }
;         __syncthreads();
;     }
.LBB0_769:
	v_readlane_b32 s4, v253, 22
	v_readlane_b32 s3, v253, 10
	s_add_i32 s6, s6, s4
	s_add_i32 s2, s2, s3
	s_cmpk_lt_i32 s6, 0x220
	s_barrier
	v_readlane_b32 s5, v253, 23
	s_cbranch_scc0 .LBB0_772
	s_branch .Ldt_have_loads

; __device__ __forceinline__ void ph_dt_tasks(Frame& F, int layer) {
;     ...
;         const bf16* ap = pA2 + (size_t)(row0 + r) * D + kq * 512 + 8 * g;
;         bf16x8 av[16];
; #pragma unroll
;         for (int ks = 0; ks < 16; ++ks) av[ks] = *(const bf16x8*)(ap + 32 * ks);
;         f32x4 a0 = {0.f, 0.f, 0.f, 0.f}, a1 = a0;
; #pragma unroll
;         for (int ks = 0; ks < 16; ++ks) { a0 = __builtin_amdgcn_mfma_f32_16x16x32_bf16(av[ks], wv0[ks], a0, 0, 0, 0); a1 = __builtin_amdgcn_mfma_f32_16x16x32_bf16(av[ks], wv1[ks], a1, 0, 0, 0); }
;         red[(wave * 2 + 0) * 64 + lane] = a0; red[(wave * 2 + 1) * 64 + lane] = a1;
;         __syncthreads();
;         if (kq == 0) {
; #pragma unroll
;             for (int k = 1; k < 4; ++k) { a0 += red[((wave + k) * 2 + 0) * 64 + lane]; a1 += red[((wave + k) * 2 + 1) * 64 + lane]; }
; #pragma unroll
;             for (int q = 0; q < 4; ++q) { float* o = pDT + (size_t)(row0 + 4 * g + q) * 32 + r; const float x0 = a0[q] + b0, x1 = a1[q] + b1;
.Ldt_have_loads:
	s_andn2_b64 vcc, exec, s[0:1]
	s_waitcnt vmcnt(14)
	v_mfma_f32_16x16x32_bf16 v[136:139], v[132:135], v[116:119], 0
	v_mfma_f32_16x16x32_bf16 v[132:135], v[132:135], v[4:7], 0
	v_mfma_f32_16x16x32_bf16 v[136:139], v[146:149], v[12:15], v[136:139]
	v_mfma_f32_16x16x32_bf16 v[132:135], v[146:149], v[8:11], v[132:135]
	s_waitcnt vmcnt(13)
	v_mfma_f32_16x16x32_bf16 v[136:139], v[172:175], v[16:19], v[136:139]
	v_mfma_f32_16x16x32_bf16 v[132:135], v[172:175], v[20:23], v[132:135]
	s_waitcnt vmcnt(12)
	v_mfma_f32_16x16x32_bf16 v[136:139], v[176:179], v[28:31], v[136:139]
	v_mfma_f32_16x16x32_bf16 v[132:135], v[176:179], v[24:27], v[132:135]
	s_waitcnt vmcnt(11)
	v_mfma_f32_16x16x32_bf16 v[136:139], v[180:183], v[32:35], v[136:139]
	v_mfma_f32_16x16x32_bf16 v[132:135], v[180:183], v[36:39], v[132:135]
	s_waitcnt vmcnt(10)
	v_mfma_f32_16x16x32_bf16 v[136:139], v[184:187], v[44:47], v[136:139]
	v_mfma_f32_16x16x32_bf16 v[132:135], v[184:187], v[40:43], v[132:135]
	s_waitcnt vmcnt(9)
	v_mfma_f32_16x16x32_bf16 v[136:139], v[188:191], v[48:51], v[136:139]
	v_mfma_f32_16x16x32_bf16 v[132:135], v[188:191], v[52:55], v[132:135]
	s_waitcnt vmcnt(8)
	v_mfma_f32_16x16x32_bf16 v[136:139], v[192:195], v[60:63], v[136:139]
	v_mfma_f32_16x16x32_bf16 v[132:135], v[192:195], v[56:59], v[132:135]
	s_waitcnt vmcnt(7)
	v_mfma_f32_16x16x32_bf16 v[136:139], v[196:199], v[64:67], v[136:139]
	v_mfma_f32_16x16x32_bf16 v[132:135], v[196:199], v[68:71], v[132:135]
	s_waitcnt vmcnt(6)
	v_mfma_f32_16x16x32_bf16 v[136:139], v[200:203], v[76:79], v[136:139]
	v_mfma_f32_16x16x32_bf16 v[132:135], v[200:203], v[72:75], v[132:135]
	s_waitcnt vmcnt(5)
	v_mfma_f32_16x16x32_bf16 v[136:139], v[204:207], v[80:83], v[136:139]
	v_mfma_f32_16x16x32_bf16 v[132:135], v[204:207], v[84:87], v[132:135]
	s_waitcnt vmcnt(4)
	v_mfma_f32_16x16x32_bf16 v[136:139], v[208:211], v[92:95], v[136:139]
	v_mfma_f32_16x16x32_bf16 v[132:135], v[208:211], v[88:91], v[132:135]
	s_waitcnt vmcnt(3)
	v_mfma_f32_16x16x32_bf16 v[136:139], v[228:231], v[96:99], v[136:139]
	v_mfma_f32_16x16x32_bf16 v[132:135], v[228:231], v[100:103], v[132:135]
	s_waitcnt vmcnt(2)
	v_mfma_f32_16x16x32_bf16 v[136:139], v[232:235], v[108:111], v[136:139]
	v_mfma_f32_16x16x32_bf16 v[132:135], v[232:235], v[104:107], v[132:135]
	s_waitcnt vmcnt(1)
	v_mfma_f32_16x16x32_bf16 v[136:139], v[236:239], v[112:115], v[136:139]
	v_mfma_f32_16x16x32_bf16 v[132:135], v[236:239], v[124:127], v[132:135]
	s_waitcnt vmcnt(0)
	v_mfma_f32_16x16x32_bf16 v[136:139], v[244:247], v[120:123], v[136:139]
	v_mfma_f32_16x16x32_bf16 v[132:135], v[244:247], v[128:131], v[132:135]
	s_nop 6
	ds_write_b128 v2, v[136:139]
	ds_write_b128 v2, v[132:135] offset:1024
	s_waitcnt lgkmcnt(0)
	v_readlane_b32 s3, v253, 22
	s_add_i32 s3, s6, s3
	s_cmpk_lt_i32 s3, 0x220
	s_cbranch_scc0 .Ldt_no_prefetch
	v_readlane_b32 s4, v253, 10
	s_add_i32 s4, s2, s4
	v_add_u32_e32 v132, s4, v140
	v_ashrrev_i32_e32 v133, 31, v132
	v_lshlrev_b64 v[132:133], 12, v[132:133]
	v_lshl_add_u64 v[152:153], v[142:143], 0, v[132:133]
	global_load_dwordx4 v[132:135], v[152:153], off
	global_load_dwordx4 v[146:149], v[152:153], off offset:64
	global_load_dwordx4 v[172:175], v[152:153], off offset:128
	global_load_dwordx4 v[176:179], v[152:153], off offset:192
	global_load_dwordx4 v[180:183], v[152:153], off offset:256
	global_load_dwordx4 v[184:187], v[152:153], off offset:320
	global_load_dwordx4 v[188:191], v[152:153], off offset:384
	global_load_dwordx4 v[192:195], v[152:153], off offset:448
	global_load_dwordx4 v[196:199], v[152:153], off offset:512
	global_load_dwordx4 v[200:203], v[152:153], off offset:576
	global_load_dwordx4 v[204:207], v[152:153], off offset:640
	global_load_dwordx4 v[208:211], v[152:153], off offset:704
	global_load_dwordx4 v[228:231], v[152:153], off offset:768
	global_load_dwordx4 v[232:235], v[152:153], off offset:832
	global_load_dwordx4 v[236:239], v[152:153], off offset:896
	global_load_dwordx4 v[244:247], v[152:153], off offset:960
.Ldt_no_prefetch:
	s_barrier
	s_lshl_b32 s3, s92, 1
	s_lshl_b32 s4, s11, 2
	s_sub_u32 s3, s3, s4
	v_subrev_u32_e32 v139, s3, v2
	ds_read_b32 v152, v139
	ds_read_b32 v153, v139 offset:2048
	ds_read_b32 v154, v139 offset:4096
	ds_read_b32 v155, v139 offset:6144
	ds_read_b32 v156, v139 offset:1024
	ds_read_b32 v157, v139 offset:3072
	ds_read_b32 v158, v139 offset:5120
	ds_read_b32 v159, v139 offset:7168
	s_mov_b32 s3, 0xbfb8aa3b
	s_mov_b32 s4, 0x3f2aaaab
	s_mov_b32 s5, 0x3f317218
	s_mov_b32 s7, 0x7f800000
	s_mov_b32 s8, 0x33800000
	s_waitcnt lgkmcnt(4)
	v_add_f32_e32 v152, v152, v153
	v_add_f32_e32 v152, v152, v154
	v_add_f32_e32 v152, v152, v155
	v_add_f32_e32 v137, v141, v152
	s_waitcnt lgkmcnt(0)
; __device__ __forceinline__ void ph_dt_tasks(Frame& F, int layer) {
;     ...
;             for (int q = 0; q < 4; ++q) { float* o = pDT + (size_t)(row0 + 4 * g + q) * 32 + r; const float x0 = a0[q] + b0, x1 = a1[q] + b1;
;                 o[0] = fmaxf(x0, 0.f) + log1pf(__expf(-fabsf(x0))); o[16] = fmaxf(x1, 0.f) + log1pf(__expf(-fabsf(x1))); }
	v_add_f32_e32 v156, v156, v157
	v_add_f32_e32 v156, v156, v158
	v_add_f32_e32 v156, v156, v159
	v_add_f32_e32 v138, v150, v156
	v_max_f32_e32 v139, 0, v137
	v_mul_f32_e64 v137, |v137|, s3
	v_exp_f32_e32 v137, v137
	s_nop 0
	v_add_f32_e32 v154, 1.0, v137
	v_add_f32_e32 v152, -1.0, v154
	v_sub_f32_e32 v153, v152, v154
	v_add_f32_e32 v153, 1.0, v153
	v_sub_f32_e32 v152, v137, v152
	v_add_f32_e32 v155, v152, v153
	v_frexp_mant_f32_e32 v152, v154
	v_cmp_gt_f32_e32 vcc, s4, v152
	v_cvt_f64_f32_e32 v[152:153], v154
	v_frexp_exp_i32_f64_e32 v152, v[152:153]
	v_subbrev_co_u32_e32 v152, vcc, 0, v152, vcc
	v_sub_u32_e32 v153, 0, v152
	v_ldexp_f32 v154, v154, v153
	v_ldexp_f32 v153, v155, v153
	v_add_f32_e32 v155, -1.0, v154
	v_add_f32_e32 v156, 1.0, v155
	v_sub_f32_e32 v156, v154, v156
	v_add_f32_e32 v156, v153, v156
	v_add_f32_e32 v157, v155, v156
	v_sub_f32_e32 v155, v157, v155
	v_sub_f32_e32 v155, v156, v155
	v_add_f32_e32 v156, 1.0, v154
	v_add_f32_e32 v158, -1.0, v156
	v_sub_f32_e32 v154, v154, v158
	v_add_f32_e32 v153, v153, v154
	v_add_f32_e32 v154, v156, v153
	v_sub_f32_e32 v156, v154, v156
	v_sub_f32_e32 v153, v153, v156
	v_rcp_f32_e32 v156, v154
	v_cvt_f32_i32_e32 v152, v152
	v_cmp_neq_f32_e32 vcc, s7, v137
	v_mul_f32_e32 v158, v157, v156
	v_mul_f32_e32 v159, v154, v158
	v_fma_f32 v160, v158, v154, -v159
	v_fmac_f32_e32 v160, v158, v153
	v_add_f32_e32 v161, v159, v160
	v_sub_f32_e32 v162, v157, v161
	v_sub_f32_e32 v157, v157, v162
	v_sub_f32_e32 v159, v161, v159
	v_sub_f32_e32 v157, v157, v161
	v_add_f32_e32 v155, v155, v157
	v_sub_f32_e32 v157, v159, v160
	v_add_f32_e32 v155, v157, v155
	v_add_f32_e32 v157, v162, v155
	v_mul_f32_e32 v159, v156, v157
	v_mul_f32_e32 v160, v154, v159
	v_fma_f32 v154, v159, v154, -v160
	v_fmac_f32_e32 v154, v159, v153
	v_sub_f32_e32 v153, v162, v157
	v_add_f32_e32 v153, v155, v153
	v_add_f32_e32 v155, v160, v154
	v_sub_f32_e32 v161, v157, v155
	v_sub_f32_e32 v157, v157, v161
	v_sub_f32_e32 v160, v155, v160
	v_sub_f32_e32 v155, v157, v155
	v_add_f32_e32 v153, v153, v155
	v_sub_f32_e32 v154, v160, v154
	v_add_f32_e32 v153, v154, v153
	v_add_f32_e32 v154, v158, v159
	v_add_f32_e32 v153, v161, v153
	v_sub_f32_e32 v155, v154, v158
	v_mul_f32_e32 v153, v156, v153
	v_sub_f32_e32 v155, v159, v155
	v_add_f32_e32 v153, v155, v153
	v_mul_f32_e32 v158, 0x3f317218, v152
	v_add_f32_e32 v155, v154, v153
	v_fma_f32 v159, v152, s5, -v158
	v_mul_f32_e32 v156, v155, v155
	v_fmac_f32_e32 v159, 0xb102e308, v152
	v_sub_f32_e32 v152, v155, v154
	v_fmamk_f32 v157, v156, 0x3e9b6dac, v215
	v_sub_f32_e32 v152, v153, v152
	v_add_f32_e32 v153, v158, v159
	v_fmaak_f32 v157, v156, v157, 0x3f2aaada
	v_sub_f32_e32 v154, v153, v158
	v_ldexp_f32 v158, v155, 1
	v_mul_f32_e32 v155, v155, v156
	v_mul_f32_e32 v155, v155, v157
	v_add_f32_e32 v156, v158, v155
	v_sub_f32_e32 v157, v156, v158
	v_ldexp_f32 v152, v152, 1
	v_sub_f32_e32 v155, v155, v157
	v_add_f32_e32 v152, v152, v155
	v_add_f32_e32 v155, v156, v152
	v_sub_f32_e32 v156, v155, v156
	v_sub_f32_e32 v152, v152, v156
	v_add_f32_e32 v156, v153, v155
	v_sub_f32_e32 v157, v156, v153
	v_sub_f32_e32 v158, v156, v157
	v_sub_f32_e32 v154, v159, v154
	v_sub_f32_e32 v153, v153, v158
	v_sub_f32_e32 v155, v155, v157
	v_add_f32_e32 v153, v155, v153
	v_add_f32_e32 v155, v154, v152
	v_sub_f32_e32 v157, v155, v154
	v_sub_f32_e32 v158, v155, v157
	v_sub_f32_e32 v154, v154, v158
	v_sub_f32_e32 v152, v152, v157
	v_add_f32_e32 v153, v155, v153
	v_add_f32_e32 v152, v152, v154
	v_add_f32_e32 v154, v156, v153
	v_sub_f32_e32 v155, v154, v156
	v_sub_f32_e32 v153, v153, v155
	v_add_f32_e32 v152, v152, v153
	v_add_f32_e32 v152, v154, v152
	v_cndmask_b32_e32 v152, v217, v152, vcc
	v_cmp_ngt_f32_e32 vcc, -1.0, v137
	s_nop 1
	v_cndmask_b32_e32 v152, v218, v152, vcc
	v_cmp_neq_f32_e32 vcc, -1.0, v137
	s_nop 1
	v_cndmask_b32_e32 v152, v219, v152, vcc
	v_cmp_lt_f32_e64 vcc, |v137|, s8
	s_nop 1
	v_cndmask_b32_e32 v137, v152, v137, vcc
	v_add_f32_e32 v137, v139, v137
	v_add_u32_e32 v152, s2, v151
	v_add_u32_e32 v152, s11, v152
	v_ashrrev_i32_e32 v153, 31, v152
	v_lshlrev_b64 v[152:153], 7, v[152:153]
	v_lshl_add_u64 v[152:153], v[144:145], 0, v[152:153]
; __device__ __forceinline__ void ph_dt_tasks(Frame& F, int layer) {
;     ...
;             for (int q = 0; q < 4; ++q) { float* o = pDT + (size_t)(row0 + 4 * g + q) * 32 + r; const float x0 = a0[q] + b0, x1 = a1[q] + b1;
;                 o[0] = fmaxf(x0, 0.f) + log1pf(__expf(-fabsf(x0))); o[16] = fmaxf(x1, 0.f) + log1pf(__expf(-fabsf(x1))); }
;         }
;         __syncthreads();
;     }
	global_store_dword v[152:153], v137, off
	v_max_f32_e32 v137, 0, v138
	v_mul_f32_e64 v138, |v138|, s3
	v_exp_f32_e32 v138, v138
	s_nop 0
	v_add_f32_e32 v139, 1.0, v138
	v_add_f32_e32 v152, -1.0, v139
	v_sub_f32_e32 v153, v152, v139
	v_add_f32_e32 v153, 1.0, v153
	v_sub_f32_e32 v152, v138, v152
	v_add_f32_e32 v154, v152, v153
	v_frexp_mant_f32_e32 v152, v139
	v_cmp_gt_f32_e32 vcc, s4, v152
	v_cvt_f64_f32_e32 v[152:153], v139
	v_frexp_exp_i32_f64_e32 v152, v[152:153]
	v_subbrev_co_u32_e32 v152, vcc, 0, v152, vcc
	v_sub_u32_e32 v153, 0, v152
	v_ldexp_f32 v139, v139, v153
	v_ldexp_f32 v153, v154, v153
	v_add_f32_e32 v154, -1.0, v139
	v_add_f32_e32 v155, 1.0, v154
	v_sub_f32_e32 v155, v139, v155
	v_add_f32_e32 v155, v153, v155
	v_add_f32_e32 v156, v154, v155
	v_sub_f32_e32 v154, v156, v154
	v_sub_f32_e32 v154, v155, v154
	v_add_f32_e32 v155, 1.0, v139
	v_add_f32_e32 v157, -1.0, v155
	v_sub_f32_e32 v139, v139, v157
	v_add_f32_e32 v139, v153, v139
	v_add_f32_e32 v153, v155, v139
	v_sub_f32_e32 v155, v153, v155
	v_sub_f32_e32 v139, v139, v155
	v_rcp_f32_e32 v155, v153
	v_cvt_f32_i32_e32 v152, v152
	v_cmp_neq_f32_e32 vcc, s7, v138
	v_mul_f32_e32 v157, v156, v155
	v_mul_f32_e32 v158, v153, v157
	v_fma_f32 v159, v157, v153, -v158
	v_fmac_f32_e32 v159, v157, v139
	v_add_f32_e32 v160, v158, v159
	v_sub_f32_e32 v161, v156, v160
	v_sub_f32_e32 v156, v156, v161
	v_sub_f32_e32 v158, v160, v158
	v_sub_f32_e32 v156, v156, v160
	v_add_f32_e32 v154, v154, v156
	v_sub_f32_e32 v156, v158, v159
	v_add_f32_e32 v154, v156, v154
	v_add_f32_e32 v156, v161, v154
	v_mul_f32_e32 v158, v155, v156
	v_mul_f32_e32 v159, v153, v158
	v_fma_f32 v153, v158, v153, -v159
	v_fmac_f32_e32 v153, v158, v139
	v_sub_f32_e32 v139, v161, v156
	v_add_f32_e32 v139, v154, v139
	v_add_f32_e32 v154, v159, v153
	v_sub_f32_e32 v160, v156, v154
	v_sub_f32_e32 v156, v156, v160
	v_sub_f32_e32 v159, v154, v159
	v_sub_f32_e32 v154, v156, v154
	v_add_f32_e32 v139, v139, v154
	v_sub_f32_e32 v153, v159, v153
	v_add_f32_e32 v139, v153, v139
	v_add_f32_e32 v153, v157, v158
	v_add_f32_e32 v139, v160, v139
	v_sub_f32_e32 v154, v153, v157
	v_mul_f32_e32 v139, v155, v139
	v_sub_f32_e32 v154, v158, v154
	v_add_f32_e32 v139, v154, v139
	v_mul_f32_e32 v157, 0x3f317218, v152
	v_add_f32_e32 v154, v153, v139
	v_fma_f32 v158, v152, s5, -v157
	v_mul_f32_e32 v155, v154, v154
	v_fmac_f32_e32 v158, 0xb102e308, v152
	v_sub_f32_e32 v152, v154, v153
	v_fmamk_f32 v156, v155, 0x3e9b6dac, v215
	v_sub_f32_e32 v139, v139, v152
	v_add_f32_e32 v152, v157, v158
	v_fmaak_f32 v156, v155, v156, 0x3f2aaada
	v_sub_f32_e32 v153, v152, v157
	v_ldexp_f32 v157, v154, 1
	v_mul_f32_e32 v154, v154, v155
	v_mul_f32_e32 v154, v154, v156
	v_add_f32_e32 v155, v157, v154
	v_sub_f32_e32 v156, v155, v157
	v_ldexp_f32 v139, v139, 1
	v_sub_f32_e32 v154, v154, v156
	v_add_f32_e32 v139, v139, v154
	v_add_f32_e32 v154, v155, v139
	v_sub_f32_e32 v155, v154, v155
	v_sub_f32_e32 v139, v139, v155
	v_add_f32_e32 v155, v152, v154
	v_sub_f32_e32 v156, v155, v152
	v_sub_f32_e32 v157, v155, v156
	v_sub_f32_e32 v153, v158, v153
	v_sub_f32_e32 v152, v152, v157
	v_sub_f32_e32 v154, v154, v156
	v_add_f32_e32 v152, v154, v152
	v_add_f32_e32 v154, v153, v139
	v_sub_f32_e32 v156, v154, v153
	v_sub_f32_e32 v157, v154, v156
	v_sub_f32_e32 v153, v153, v157
	v_sub_f32_e32 v139, v139, v156
	v_add_f32_e32 v152, v154, v152
	v_add_f32_e32 v139, v139, v153
	v_add_f32_e32 v153, v155, v152
	v_sub_f32_e32 v154, v153, v155
	v_sub_f32_e32 v152, v152, v154
	v_add_f32_e32 v139, v139, v152
	v_add_f32_e32 v139, v153, v139
	v_cndmask_b32_e32 v139, v217, v139, vcc
	v_cmp_ngt_f32_e32 vcc, -1.0, v138
	s_nop 1
	v_cndmask_b32_e32 v139, v218, v139, vcc
	v_cmp_neq_f32_e32 vcc, -1.0, v138
	s_nop 1
	v_cndmask_b32_e32 v139, v219, v139, vcc
	v_cmp_lt_f32_e64 vcc, |v138|, s8
	s_nop 1
	v_cndmask_b32_e32 v138, v139, v138, vcc
	v_add_f32_e32 v137, v137, v138
	v_add_u32_e32 v152, s2, v151
	v_add_u32_e32 v152, s11, v152
	v_ashrrev_i32_e32 v153, 31, v152
	v_lshlrev_b64 v[152:153], 7, v[152:153]
	v_lshl_add_u64 v[152:153], v[144:145], 0, v[152:153]
	global_store_dword v[152:153], v137, off offset:64
	s_branch .LBB0_769
